# LayerNorm Z loads nt (read-once) on top of the sc1 nt GEMM stores
# baseline (speedup 1.0000x reference)
; DI void phase_ln(const P& p, int l) {
;     ...
;   for (int row = r0; row < r1; row += 2) {
;     const bool two = row + 1 < r1;
;     const int rowb = two ? row + 1 : row;
;     float4 v[2][4];
; #pragma unroll
;     for (int i = 0; i < 4; ++i) {
;       v[0][i] = *(const float4*)(Zb + (size_t)row * 1024 + i * 256 + lane * 4);
;       v[1][i] = *(const float4*)(Zb + (size_t)rowb * 1024 + i * 256 + lane * 4);
;     }
; #pragma unroll
;     for (int h = 0; h < 2; ++h) {
;       if (h && !two) break;
;       const int rr = h ? rowb : row;
;       float s = 0.f;
; #pragma unroll
;       for (int i = 0; i < 4; ++i) s += (v[h][i].x + v[h][i].y) + (v[h][i].z + v[h][i].w);
; #pragma unroll
;       for (int o = 32; o >= 1; o >>= 1) s += __shfl_xor(s, o);
;       const float mean = s * (1.f / 1024.f);
;       float q = 0.f;
; #pragma unroll
;       for (int i = 0; i < 4; ++i) {
;         v[h][i].x -= mean; v[h][i].y -= mean; v[h][i].z -= mean; v[h][i].w -= mean;
;         q += (v[h][i].x * v[h][i].x + v[h][i].y * v[h][i].y) + (v[h][i].z * v[h][i].z + v[h][i].w * v[h][i].w);
;       }
; #pragma unroll
;       for (int o = 32; o >= 1; o >>= 1) q += __shfl_xor(q, o);
;       const float rstd = rsqrtf(q * (1.f / 1024.f) + 1e-5f);
;       const int mr = rr < MLAT ? (rr >> 11) : 16;
;       const float* md = p.mod + (size_t)(1 * 17 + mr) * 3072;
; #pragma unroll
;       for (int i = 0; i < 4; ++i) {
;         const int col = i * 256 + lane * 4;
;         float4 y;
;         y.x = v[h][i].x * rstd * g4[i].x + b4[i].x;
;         y.y = v[h][i].y * rstd * g4[i].y + b4[i].y;
;         y.z = v[h][i].z * rstd * g4[i].z + b4[i].z;
;         y.w = v[h][i].w * rstd * g4[i].w + b4[i].w;
;         if (l == 1 || rr < MLAT) *(float4*)(p.out + (size_t)rr * 1024 + col) = y;
.Lln_nopf:
	v_add_u32_e32 v63, 1, v62
	v_cmp_lt_i32_e64 s[40:41], v63, v65
	v_lshl_add_u64 v[90:91], v[80:81], 0, v[78:79]
	v_cmp_gt_i32_e32 vcc, s21, v62
	v_cndmask_b32_e64 v86, v62, v63, s[40:41]
	v_ashrrev_i32_e32 v87, 31, v86
	v_lshlrev_b64 v[88:89], 12, v[86:87]
	v_lshl_add_u64 v[38:39], v[66:67], 0, v[88:89]
	global_load_dwordx4 v[34:37], v[38:39], off nt
	global_load_dwordx4 v[46:49], v[38:39], off offset:1024 nt
	global_load_dwordx4 v[42:45], v[38:39], off offset:2048 nt
	s_nop 0
	global_load_dwordx4 v[38:41], v[38:39], off offset:3072 nt
	s_nop 0
	global_load_dwordx4 v[50:53], v[90:91], off offset:3072 nt
	global_load_dwordx4 v[54:57], v[90:91], off offset:2048 nt
	global_load_dwordx4 v[58:61], v[90:91], off offset:1024 nt
	s_or_b64 s[52:53], s[46:47], vcc
	s_waitcnt vmcnt(1)
	v_mov_b32_e32 v0, v57
	s_waitcnt vmcnt(0)
	v_mov_b32_e32 v92, v58
	v_mov_b32_e32 v93, v60
	v_mov_b32_e32 v98, v59
	v_mov_b32_e32 v99, v61
	v_pk_add_f32 v[92:93], v[92:93], v[98:99]
	v_pk_add_f32 v[94:95], v[56:57], v[0:1]
	v_pk_add_f32 v[98:99], v[92:93], v[92:93] op_sel:[0,1] op_sel_hi:[1,0]
	global_load_dwordx4 v[90:93], v[90:91], off nt
	v_mov_b32_e32 v0, v55
	v_pk_add_f32 v[96:97], v[54:55], v[0:1]
	v_mov_b32_e32 v95, v53
	v_mov_b32_e32 v97, v52
	v_mov_b32_e32 v99, v51
	v_pk_add_f32 v[94:95], v[96:97], v[94:95]
	s_waitcnt vmcnt(0)
	v_mov_b32_e32 v100, v90
	v_mov_b32_e32 v101, v92
	v_mov_b32_e32 v106, v91
	v_mov_b32_e32 v107, v93
	v_pk_add_f32 v[100:101], v[100:101], v[106:107]
	s_nop 0
	v_add_f32_e32 v0, v100, v101
	v_add_f32_e32 v100, 0, v0
	v_mov_b32_e32 v101, v50
	v_pk_add_f32 v[96:97], v[100:101], v[98:99]
	s_nop 0
	v_pk_add_f32 v[94:95], v[96:97], v[94:95]
	s_nop 0
	v_add_f32_e32 v0, v94, v95
	v_mov_b32_e32 v94, v0
	s_nop 1
	v_permlane32_swap_b32_e32 v0, v94
	v_add_f32_e32 v0, v0, v94
	v_mov_b32_e32 v94, v0
	s_nop 1
	v_permlane16_swap_b32_e32 v0, v94
	v_add_f32_e32 v0, v0, v94
	s_nop 1
	v_add_f32_dpp v0, v0, v0 row_ror:8 row_mask:0xf bank_mask:0xf
	s_nop 1
	v_mov_b32_dpp v94, v0 row_shl:4 row_mask:0xf bank_mask:0x5
	v_mov_b32_dpp v94, v0 row_shr:4 row_mask:0xf bank_mask:0xa
	v_add_f32_e32 v0, v0, v94
	s_nop 1
	v_add_f32_dpp v0, v0, v0 quad_perm:[2,3,0,1] row_mask:0xf bank_mask:0xf
	s_nop 1
	v_add_f32_dpp v0, v0, v0 quad_perm:[1,0,3,2] row_mask:0xf bank_mask:0xf
	v_mul_f32_e32 v0, 0x3a800000, v0
	v_pk_add_f32 v[96:97], v[90:91], v[0:1] op_sel_hi:[1,0] neg_lo:[0,1] neg_hi:[0,1]
	v_pk_add_f32 v[98:99], v[92:93], v[0:1] op_sel_hi:[1,0] neg_lo:[0,1] neg_hi:[0,1]
	v_mov_b32_e32 v92, v97
	v_mov_b32_e32 v93, v99
	v_mov_b32_e32 v90, v96
	v_mov_b32_e32 v91, v98
	v_pk_mul_f32 v[92:93], v[92:93], v[92:93]
	s_nop 0
	v_pk_fma_f32 v[90:91], v[90:91], v[90:91], v[92:93]
	v_pk_add_f32 v[92:93], v[58:59], v[0:1] op_sel_hi:[1,0] neg_lo:[0,1] neg_hi:[0,1]
	v_pk_add_f32 v[94:95], v[90:91], v[90:91] op_sel_hi:[0,1]
	v_pk_add_f32 v[90:91], v[60:61], v[0:1] op_sel_hi:[1,0] neg_lo:[0,1] neg_hi:[0,1]
	v_mov_b32_e32 v60, v93
	v_mov_b32_e32 v61, v91
	v_mov_b32_e32 v58, v92
	v_mov_b32_e32 v59, v90
	v_pk_mul_f32 v[60:61], v[60:61], v[60:61]
	s_nop 0
	v_pk_fma_f32 v[58:59], v[58:59], v[58:59], v[60:61]
	v_pk_add_f32 v[60:61], v[54:55], v[0:1] op_sel_hi:[1,0] neg_lo:[0,1] neg_hi:[0,1]
	v_pk_add_f32 v[100:101], v[58:59], v[58:59] op_sel_hi:[0,1]
	v_pk_add_f32 v[58:59], v[56:57], v[0:1] op_sel_hi:[1,0] neg_lo:[0,1] neg_hi:[0,1]
	v_mul_f32_e32 v54, v60, v60
	v_pk_fma_f32 v[106:107], v[60:61], v[60:61], v[54:55] op_sel_hi:[1,1,0]
	v_mul_f32_e32 v54, v58, v58
	v_pk_fma_f32 v[108:109], v[58:59], v[58:59], v[54:55] op_sel_hi:[1,1,0]
	v_pk_add_f32 v[56:57], v[50:51], v[0:1] op_sel_hi:[1,0] neg_lo:[0,1] neg_hi:[0,1]
	v_pk_add_f32 v[54:55], v[52:53], v[0:1] op_sel_hi:[1,0] neg_lo:[0,1] neg_hi:[0,1]
	v_pk_mul_f32 v[50:51], v[56:57], v[56:57]
	v_pk_mul_f32 v[52:53], v[54:55], v[54:55]
	v_mov_b32_e32 v106, v50
	v_mov_b32_e32 v108, v51
	v_mov_b32_e32 v94, v52
	v_mov_b32_e32 v100, v53
	v_pk_add_f32 v[50:51], v[106:107], v[108:109]
	v_pk_add_f32 v[52:53], v[94:95], v[100:101]
	s_nop 0
	v_pk_add_f32 v[50:51], v[50:51], v[52:53]
	s_nop 0
	v_add_f32_e32 v0, v50, v51
	v_mov_b32_e32 v50, v0
	s_nop 1
	v_permlane32_swap_b32_e32 v0, v50
	v_add_f32_e32 v0, v0, v50
	v_mov_b32_e32 v50, v0
	s_nop 1
	v_permlane16_swap_b32_e32 v0, v50
	v_add_f32_e32 v0, v0, v50
	s_nop 1
	v_add_f32_dpp v0, v0, v0 row_ror:8 row_mask:0xf bank_mask:0xf
	s_nop 1
	v_mov_b32_dpp v50, v0 row_shl:4 row_mask:0xf bank_mask:0x5
	v_mov_b32_dpp v50, v0 row_shr:4 row_mask:0xf bank_mask:0xa
	v_add_f32_e32 v0, v0, v50
	s_nop 1
	v_add_f32_dpp v0, v0, v0 quad_perm:[2,3,0,1] row_mask:0xf bank_mask:0xf
	s_nop 1
	v_add_f32_dpp v0, v0, v0 quad_perm:[1,0,3,2] row_mask:0xf bank_mask:0xf
	v_mov_b32_e32 v50, 0x3727c5ac
	v_fmamk_f32 v0, v0, 0x3a800000, v50
	v_cmp_gt_f32_e32 vcc, s37, v0
	v_mul_f32_e32 v50, 0x4b800000, v0
	s_nop 0
	v_cndmask_b32_e32 v0, v0, v50, vcc
	v_rsq_f32_e32 v0, v0
	s_nop 0
	v_mul_f32_e32 v50, 0x45800000, v0
	v_cndmask_b32_e32 v94, v0, v50, vcc
	v_pk_mul_f32 v[50:51], v[96:97], v[94:95] op_sel_hi:[1,0]
	v_pk_mul_f32 v[52:53], v[98:99], v[94:95] op_sel_hi:[1,0]
	v_pk_fma_f32 v[50:51], v[2:3], v[50:51], v[10:11]
	v_pk_fma_f32 v[52:53], v[4:5], v[52:53], v[12:13]
	v_lshl_add_u64 v[96:97], v[82:83], 0, v[78:79]
	s_and_saveexec_b64 s[42:43], s[52:53]
	s_cbranch_execz .LBB0_34
	global_store_dwordx4 v[96:97], v[50:53], off
